# grid barrier poll loop sleeps longer between polls (s_sleep 6): fewer polls in flight against the arrival counter, less idle power
# speedup vs baseline: 1.0027x; 1.0027x over previous
.Lmy_bar_loop:
	global_load_dword v0, v33, s[2:3] sc1
	s_waitcnt vmcnt(0)
	v_cmp_lt_u32_e32 vcc, v0, v6
	s_cbranch_vccz .Lmy_bar_done
	s_sleep 6
	s_add_i32 s0, s0, 1
	s_and_b32 s30, s0, 0xff
	s_cmp_lg_u32 s30, 0
	s_cbranch_scc1 .Lmy_bar_loop
	v_readlane_b32 s30, v253, 25
	v_readlane_b32 s31, v253, 26
	s_nop 4
	global_load_dword v0, v33, s[30:31] sc1
	s_waitcnt vmcnt(0)
	v_cmp_ne_u32_e32 vcc, 0, v0
	s_cbranch_vccnz .Lmy_bar_done
	s_cmp_lt_u32 s0, 0x40001
	s_cbranch_scc1 .Lmy_bar_loop
	global_atomic_add v33, v179, s[30:31]
